# SSD M=CB*decay stage rewritten: per-tile batched fcs LDS reads (4x b128) and branch-free masked rows instead of 16 serialized read-wait-exp rows
# speedup vs baseline: 1.0078x; 1.0078x over previous
; __device__ __forceinline__ unsigned short f2bf(float f) { return (unsigned short)(cvt_pk_bf16(f, 0.f) & 0xffffu); }
; __device__ __forceinline__ void ssd_item(const Params& p, LAS unsigned char* lds, int bl, int head, int dry) {
;     ...
; #pragma unroll
;         for (int q = 0; q < 2; ++q) if (tj[q] <= ti[q]) {
;             const int s = tj[q] * 32 + cl; const float css = fcs[s];
; #pragma unroll
;             for (int r = 0; r < 16; ++r) { const int l = ti[q] * 32 + (r & 3) + 8 * (r >> 2) + rsub;
;                 const float mv = (s <= l) ? cb[q][r] * __expf(fcs[l] - css) : 0.f; BMm[l * SLD + s] = f2bf(mv); } }
.LBB0_246:
	s_or_b64 exec, exec, s[56:57]
	v_lshl_add_u32 v158, v179, 2, s63
	s_barrier
	ds_read_b32 v159, v158
	s_and_saveexec_b64 s[56:57], s[46:47]
	s_cbranch_execz .Lm_t1_done
	v_lshl_add_u32 v194, v167, 2, s63
	ds_read_b128 v[198:201], v194
	ds_read_b128 v[202:205], v194 offset:32
	ds_read_b128 v[206:209], v194 offset:64
	ds_read_b128 v[210:213], v194 offset:96
	v_sub_u32_e32 v195, v179, v167
	v_add_u32_e32 v196, v180, v177
	s_waitcnt lgkmcnt(0)
	v_sub_f32_e32 v198, v198, v159
	v_sub_f32_e32 v199, v199, v159
	v_sub_f32_e32 v200, v200, v159
	v_sub_f32_e32 v201, v201, v159
	v_sub_f32_e32 v202, v202, v159
	v_sub_f32_e32 v203, v203, v159
	v_sub_f32_e32 v204, v204, v159
	v_sub_f32_e32 v205, v205, v159
	v_sub_f32_e32 v206, v206, v159
	v_sub_f32_e32 v207, v207, v159
	v_sub_f32_e32 v208, v208, v159
	v_sub_f32_e32 v209, v209, v159
	v_sub_f32_e32 v210, v210, v159
	v_sub_f32_e32 v211, v211, v159
	v_sub_f32_e32 v212, v212, v159
	v_sub_f32_e32 v213, v213, v159
	v_mul_f32_e32 v198, 0x3fb8aa3b, v198
	v_mul_f32_e32 v199, 0x3fb8aa3b, v199
	v_mul_f32_e32 v200, 0x3fb8aa3b, v200
	v_mul_f32_e32 v201, 0x3fb8aa3b, v201
	v_mul_f32_e32 v202, 0x3fb8aa3b, v202
	v_mul_f32_e32 v203, 0x3fb8aa3b, v203
	v_mul_f32_e32 v204, 0x3fb8aa3b, v204
	v_mul_f32_e32 v205, 0x3fb8aa3b, v205
	v_mul_f32_e32 v206, 0x3fb8aa3b, v206
	v_mul_f32_e32 v207, 0x3fb8aa3b, v207
	v_mul_f32_e32 v208, 0x3fb8aa3b, v208
	v_mul_f32_e32 v209, 0x3fb8aa3b, v209
	v_mul_f32_e32 v210, 0x3fb8aa3b, v210
	v_mul_f32_e32 v211, 0x3fb8aa3b, v211
	v_mul_f32_e32 v212, 0x3fb8aa3b, v212
	v_mul_f32_e32 v213, 0x3fb8aa3b, v213
	v_exp_f32_e32 v198, v198
	v_exp_f32_e32 v199, v199
	v_exp_f32_e32 v200, v200
	v_exp_f32_e32 v201, v201
	v_exp_f32_e32 v202, v202
	v_exp_f32_e32 v203, v203
	v_exp_f32_e32 v204, v204
	v_exp_f32_e32 v205, v205
	v_exp_f32_e32 v206, v206
	v_exp_f32_e32 v207, v207
	v_exp_f32_e32 v208, v208
	v_exp_f32_e32 v209, v209
	v_exp_f32_e32 v210, v210
	v_exp_f32_e32 v211, v211
	v_exp_f32_e32 v212, v212
	v_exp_f32_e32 v213, v213
	v_cmp_ge_i32_e32 vcc, 0, v195
	v_mul_f32_e32 v32, v32, v198
	v_cmp_ge_i32_e64 s[58:59], 1, v195
	v_mul_f32_e32 v33, v33, v199
	v_cndmask_b32_e32 v32, v169, v32, vcc
	v_cndmask_b32_e64 v33, 0, v33, s[58:59]
	v_cvt_pk_bf16_f32 v32, v32, v169
	v_cvt_pk_bf16_f32 v33, v33, v169
	ds_write_b16 v196, v32 offset:34816
	ds_write_b16 v196, v33 offset:35088
	v_cmp_ge_i32_e32 vcc, 2, v195
	v_mul_f32_e32 v34, v34, v200
	v_cmp_ge_i32_e64 s[58:59], 3, v195
	v_mul_f32_e32 v35, v35, v201
	v_cndmask_b32_e32 v34, v169, v34, vcc
	v_cndmask_b32_e64 v35, 0, v35, s[58:59]
	v_cvt_pk_bf16_f32 v34, v34, v169
	v_cvt_pk_bf16_f32 v35, v35, v169
	ds_write_b16 v196, v34 offset:35360
	ds_write_b16 v196, v35 offset:35632
	v_cmp_ge_i32_e32 vcc, 8, v195
	v_mul_f32_e32 v36, v36, v202
	v_cmp_ge_i32_e64 s[58:59], 9, v195
	v_mul_f32_e32 v37, v37, v203
	v_cndmask_b32_e32 v36, v169, v36, vcc
	v_cndmask_b32_e64 v37, 0, v37, s[58:59]
	v_cvt_pk_bf16_f32 v36, v36, v169
	v_cvt_pk_bf16_f32 v37, v37, v169
	ds_write_b16 v196, v36 offset:36992
	ds_write_b16 v196, v37 offset:37264
	v_cmp_ge_i32_e32 vcc, 10, v195
	v_mul_f32_e32 v38, v38, v204
	v_cmp_ge_i32_e64 s[58:59], 11, v195
	v_mul_f32_e32 v39, v39, v205
	v_cndmask_b32_e32 v38, v169, v38, vcc
	v_cndmask_b32_e64 v39, 0, v39, s[58:59]
	v_cvt_pk_bf16_f32 v38, v38, v169
	v_cvt_pk_bf16_f32 v39, v39, v169
	ds_write_b16 v196, v38 offset:37536
	ds_write_b16 v196, v39 offset:37808
	v_cmp_ge_i32_e32 vcc, 16, v195
	v_mul_f32_e32 v40, v40, v206
	v_cmp_ge_i32_e64 s[58:59], 17, v195
	v_mul_f32_e32 v41, v41, v207
	v_cndmask_b32_e32 v40, v169, v40, vcc
	v_cndmask_b32_e64 v41, 0, v41, s[58:59]
	v_cvt_pk_bf16_f32 v40, v40, v169
	v_cvt_pk_bf16_f32 v41, v41, v169
	ds_write_b16 v196, v40 offset:39168
	ds_write_b16 v196, v41 offset:39440
	v_cmp_ge_i32_e32 vcc, 18, v195
	v_mul_f32_e32 v42, v42, v208
	v_cmp_ge_i32_e64 s[58:59], 19, v195
	v_mul_f32_e32 v43, v43, v209
	v_cndmask_b32_e32 v42, v169, v42, vcc
	v_cndmask_b32_e64 v43, 0, v43, s[58:59]
	v_cvt_pk_bf16_f32 v42, v42, v169
	v_cvt_pk_bf16_f32 v43, v43, v169
	ds_write_b16 v196, v42 offset:39712
	ds_write_b16 v196, v43 offset:39984
	v_cmp_ge_i32_e32 vcc, 24, v195
	v_mul_f32_e32 v44, v44, v210
	v_cmp_ge_i32_e64 s[58:59], 25, v195
	v_mul_f32_e32 v45, v45, v211
	v_cndmask_b32_e32 v44, v169, v44, vcc
	v_cndmask_b32_e64 v45, 0, v45, s[58:59]
	v_cvt_pk_bf16_f32 v44, v44, v169
	v_cvt_pk_bf16_f32 v45, v45, v169
	ds_write_b16 v196, v44 offset:41344
	ds_write_b16 v196, v45 offset:41616
	v_cmp_ge_i32_e32 vcc, 26, v195
	v_mul_f32_e32 v46, v46, v212
	v_cmp_ge_i32_e64 s[58:59], 27, v195
	v_mul_f32_e32 v47, v47, v213
	v_cndmask_b32_e32 v46, v169, v46, vcc
	v_cndmask_b32_e64 v47, 0, v47, s[58:59]
	v_cvt_pk_bf16_f32 v46, v46, v169
	v_cvt_pk_bf16_f32 v47, v47, v169
	ds_write_b16 v196, v46 offset:41888
	ds_write_b16 v196, v47 offset:42160
; __device__ __forceinline__ unsigned short f2bf(float f) { return (unsigned short)(cvt_pk_bf16(f, 0.f) & 0xffffu); }
; __device__ __forceinline__ void ssd_item(const Params& p, LAS unsigned char* lds, int bl, int head, int dry) {
;     ...
; #pragma unroll
;         for (int q = 0; q < 2; ++q) if (tj[q] <= ti[q]) {
;             const int s = tj[q] * 32 + cl; const float css = fcs[s];
; #pragma unroll
;             for (int r = 0; r < 16; ++r) { const int l = ti[q] * 32 + (r & 3) + 8 * (r >> 2) + rsub;
;                 const float mv = (s <= l) ? cb[q][r] * __expf(fcs[l] - css) : 0.f; BMm[l * SLD + s] = f2bf(mv); } }
.Lm_t1_done:
	s_or_b64 exec, exec, s[56:57]
	s_and_saveexec_b64 s[56:57], s[48:49]
	s_cbranch_execz .Lm_t2_done
	v_lshl_add_u32 v194, v181, 2, s63
	ds_read_b128 v[198:201], v194
	ds_read_b128 v[202:205], v194 offset:32
	ds_read_b128 v[206:209], v194 offset:64
	ds_read_b128 v[210:213], v194 offset:96
	v_sub_u32_e32 v195, v179, v181
	s_waitcnt lgkmcnt(0)
	v_sub_f32_e32 v198, v198, v159
	v_sub_f32_e32 v199, v199, v159
	v_sub_f32_e32 v200, v200, v159
	v_sub_f32_e32 v201, v201, v159
	v_sub_f32_e32 v202, v202, v159
	v_sub_f32_e32 v203, v203, v159
	v_sub_f32_e32 v204, v204, v159
	v_sub_f32_e32 v205, v205, v159
	v_sub_f32_e32 v206, v206, v159
	v_sub_f32_e32 v207, v207, v159
	v_sub_f32_e32 v208, v208, v159
	v_sub_f32_e32 v209, v209, v159
	v_sub_f32_e32 v210, v210, v159
	v_sub_f32_e32 v211, v211, v159
	v_sub_f32_e32 v212, v212, v159
	v_sub_f32_e32 v213, v213, v159
	v_mul_f32_e32 v198, 0x3fb8aa3b, v198
	v_mul_f32_e32 v199, 0x3fb8aa3b, v199
	v_mul_f32_e32 v200, 0x3fb8aa3b, v200
	v_mul_f32_e32 v201, 0x3fb8aa3b, v201
	v_mul_f32_e32 v202, 0x3fb8aa3b, v202
	v_mul_f32_e32 v203, 0x3fb8aa3b, v203
	v_mul_f32_e32 v204, 0x3fb8aa3b, v204
	v_mul_f32_e32 v205, 0x3fb8aa3b, v205
	v_mul_f32_e32 v206, 0x3fb8aa3b, v206
	v_mul_f32_e32 v207, 0x3fb8aa3b, v207
	v_mul_f32_e32 v208, 0x3fb8aa3b, v208
	v_mul_f32_e32 v209, 0x3fb8aa3b, v209
	v_mul_f32_e32 v210, 0x3fb8aa3b, v210
	v_mul_f32_e32 v211, 0x3fb8aa3b, v211
	v_mul_f32_e32 v212, 0x3fb8aa3b, v212
	v_mul_f32_e32 v213, 0x3fb8aa3b, v213
	v_exp_f32_e32 v198, v198
	v_exp_f32_e32 v199, v199
	v_exp_f32_e32 v200, v200
	v_exp_f32_e32 v201, v201
	v_exp_f32_e32 v202, v202
	v_exp_f32_e32 v203, v203
	v_exp_f32_e32 v204, v204
	v_exp_f32_e32 v205, v205
	v_exp_f32_e32 v206, v206
	v_exp_f32_e32 v207, v207
	v_exp_f32_e32 v208, v208
	v_exp_f32_e32 v209, v209
	v_exp_f32_e32 v210, v210
	v_exp_f32_e32 v211, v211
	v_exp_f32_e32 v212, v212
	v_exp_f32_e32 v213, v213
	v_cmp_ge_i32_e32 vcc, 0, v195
	v_mul_f32_e32 v16, v16, v198
	v_cmp_ge_i32_e64 s[58:59], 1, v195
	v_mul_f32_e32 v17, v17, v199
	v_cndmask_b32_e32 v16, v169, v16, vcc
	v_cndmask_b32_e64 v17, 0, v17, s[58:59]
	v_cvt_pk_bf16_f32 v16, v16, v169
	v_cvt_pk_bf16_f32 v17, v17, v169
	ds_write_b16 v193, v16 offset:34816
	ds_write_b16 v193, v17 offset:35088
	v_cmp_ge_i32_e32 vcc, 2, v195
	v_mul_f32_e32 v18, v18, v200
	v_cmp_ge_i32_e64 s[58:59], 3, v195
	v_mul_f32_e32 v19, v19, v201
	v_cndmask_b32_e32 v18, v169, v18, vcc
	v_cndmask_b32_e64 v19, 0, v19, s[58:59]
	v_cvt_pk_bf16_f32 v18, v18, v169
	v_cvt_pk_bf16_f32 v19, v19, v169
	ds_write_b16 v193, v18 offset:35360
	ds_write_b16 v193, v19 offset:35632
	v_cmp_ge_i32_e32 vcc, 8, v195
	v_mul_f32_e32 v20, v20, v202
	v_cmp_ge_i32_e64 s[58:59], 9, v195
	v_mul_f32_e32 v21, v21, v203
	v_cndmask_b32_e32 v20, v169, v20, vcc
	v_cndmask_b32_e64 v21, 0, v21, s[58:59]
	v_cvt_pk_bf16_f32 v20, v20, v169
	v_cvt_pk_bf16_f32 v21, v21, v169
	ds_write_b16 v193, v20 offset:36992
	ds_write_b16 v193, v21 offset:37264
	v_cmp_ge_i32_e32 vcc, 10, v195
	v_mul_f32_e32 v22, v22, v204
	v_cmp_ge_i32_e64 s[58:59], 11, v195
	v_mul_f32_e32 v23, v23, v205
	v_cndmask_b32_e32 v22, v169, v22, vcc
	v_cndmask_b32_e64 v23, 0, v23, s[58:59]
	v_cvt_pk_bf16_f32 v22, v22, v169
	v_cvt_pk_bf16_f32 v23, v23, v169
	ds_write_b16 v193, v22 offset:37536
	ds_write_b16 v193, v23 offset:37808
	v_cmp_ge_i32_e32 vcc, 16, v195
	v_mul_f32_e32 v24, v24, v206
	v_cmp_ge_i32_e64 s[58:59], 17, v195
	v_mul_f32_e32 v25, v25, v207
	v_cndmask_b32_e32 v24, v169, v24, vcc
	v_cndmask_b32_e64 v25, 0, v25, s[58:59]
	v_cvt_pk_bf16_f32 v24, v24, v169
	v_cvt_pk_bf16_f32 v25, v25, v169
	ds_write_b16 v193, v24 offset:39168
	ds_write_b16 v193, v25 offset:39440
	v_cmp_ge_i32_e32 vcc, 18, v195
	v_mul_f32_e32 v26, v26, v208
	v_cmp_ge_i32_e64 s[58:59], 19, v195
	v_mul_f32_e32 v27, v27, v209
	v_cndmask_b32_e32 v26, v169, v26, vcc
	v_cndmask_b32_e64 v27, 0, v27, s[58:59]
	v_cvt_pk_bf16_f32 v26, v26, v169
	v_cvt_pk_bf16_f32 v27, v27, v169
	ds_write_b16 v193, v26 offset:39712
	ds_write_b16 v193, v27 offset:39984
	v_cmp_ge_i32_e32 vcc, 24, v195
	v_mul_f32_e32 v28, v28, v210
	v_cmp_ge_i32_e64 s[58:59], 25, v195
	v_mul_f32_e32 v29, v29, v211
	v_cndmask_b32_e32 v28, v169, v28, vcc
	v_cndmask_b32_e64 v29, 0, v29, s[58:59]
	v_cvt_pk_bf16_f32 v28, v28, v169
	v_cvt_pk_bf16_f32 v29, v29, v169
	ds_write_b16 v193, v28 offset:41344
	ds_write_b16 v193, v29 offset:41616
	v_cmp_ge_i32_e32 vcc, 26, v195
	v_mul_f32_e32 v30, v30, v212
	v_cmp_ge_i32_e64 s[58:59], 27, v195
	v_mul_f32_e32 v31, v31, v213
	v_cndmask_b32_e32 v30, v169, v30, vcc
	v_cndmask_b32_e64 v31, 0, v31, s[58:59]
	v_cvt_pk_bf16_f32 v30, v30, v169
	v_cvt_pk_bf16_f32 v31, v31, v169
	ds_write_b16 v193, v30 offset:41888
	ds_write_b16 v193, v31 offset:42160
.Lm_t2_done:
.LBB0_248:
	s_or_b64 exec, exec, s[56:57]
	s_nor_b64 s[0:1], s[42:43], s[0:1]
	s_and_saveexec_b64 s[56:57], s[0:1]
	s_cbranch_execnz .LBB0_315
	s_branch .LBB0_324
